# same weight-transpose deferral, work split by need: layer 0/1 weights in the first even in-projection's idle round, layer 2/3 weights in the first odd in-projection's idle round (at most three items p
# baseline (speedup 1.0000x reference)
; #define LAS __attribute__((address_space(3)))
; __device__ __forceinline__ unsigned pk2(float lo, float hi) { return f2bf(lo) | (f2bf(hi) << 16); }
; __device__ __forceinline__ void p0_transpose_item(const float* W, int K, int N, bf16_t* WT, LAS float* scr, int item, int lane) {
;     const int nblk = N / 32, kb = item / nblk, nb = item % nblk, k0 = 64 * kb, n0 = 32 * nb;
;     float tv[32];
; #pragma unroll
;     for (int i = 0; i < 32; ++i) tv[i] = W[(size_t)(k0 + 2 * i + (lane >> 5)) * N + n0 + (lane & 31)];
; #pragma unroll
;     for (int i = 0; i < 32; ++i) scr[(2 * i + (lane >> 5)) * 33 + (lane & 31)] = tv[i];
;     asm volatile("s_waitcnt lgkmcnt(0)" ::: "memory");
;     const int c = lane & 7;
; #pragma unroll
;     for (int j = 0; j < 4; ++j) { const int n = (lane >> 3) + 8 * j; const LAS float* s = scr + (8 * c) * 33 + n;
;         u32x4 o; o.x = pk2(s[0 * 33], s[1 * 33]); o.y = pk2(s[2 * 33], s[3 * 33]); o.z = pk2(s[4 * 33], s[5 * 33]); o.w = pk2(s[6 * 33], s[7 * 33]);
;         *(u32x4*)(WT + (size_t)(n0 + n) * K + k0 + 8 * c) = o; }
;     asm volatile("s_waitcnt lgkmcnt(0)" ::: "memory");
; }
; __device__ __forceinline__ void phase0(const Params& p, LAS unsigned char* lds, int gw, int NGW, int wave, int lane) {
;     ...
;     for (int it = gw; it < NIT; it += NGW) {
;         int r = it;
;         if (r < 2 * I_EI) { const int j = r / I_EI; p0_transpose_item(p.in[8] + (size_t)j * 1024 * EIN, 1024, EIN, (bf16_t*)(ws + WS_WEI) + (size_t)j * EINP * 1024, scr, r % I_EI, lane); continue; } r -= 2 * I_EI;
;         if (r < 2 * I_EO) { const int j = r / I_EO; p0_transpose_item(p.in[9] + (size_t)j * 1024 * 1024, 1024, 1024, (bf16_t*)(ws + WS_WEO) + (size_t)j * 1024 * 1024, scr, r % I_EO, lane); continue; } r -= 2 * I_EO;
;         if (r < 2 * I_OI) { const int j = r / I_OI; p0_transpose_item(p.in[21] + (size_t)j * 1024 * OIN, 1024, OIN, (bf16_t*)(ws + WS_WOI) + (size_t)j * OIN * 1024, scr, r % I_OI, lane); continue; } r -= 2 * I_OI;
;         { const int j = r / I_OO; p0_transpose_item(p.in[22] + (size_t)j * 512 * 1024, 512, 1024, (bf16_t*)(ws + WS_WOO) + (size_t)j * 1024 * 512, scr, r % I_OO, lane); }
;     }
.Lwt_o_loop:
	v_readfirstlane_b32 s100, v0
	s_nop 1
	s_cmp_ge_u32 s100, 5440
	s_cbranch_scc1 .Lkvc_o_done
	s_cmp_lt_u32 s100, 2112
	s_cbranch_scc1 .Lwt_o_c0
	s_cmp_lt_u32 s100, 2624
	s_cbranch_scc1 .Lwt_o_c1
	s_cmp_lt_u32 s100, 5184
	s_cbranch_scc1 .Lwt_o_c2
	s_branch .Lwt_o_c3

; #define LAS __attribute__((address_space(3)))
; __device__ __forceinline__ unsigned pk2(float lo, float hi) { return f2bf(lo) | (f2bf(hi) << 16); }
; __device__ __forceinline__ void p0_transpose_item(const float* W, int K, int N, bf16_t* WT, LAS float* scr, int item, int lane) {
;     const int nblk = N / 32, kb = item / nblk, nb = item % nblk, k0 = 64 * kb, n0 = 32 * nb;
;     float tv[32];
; #pragma unroll
;     for (int i = 0; i < 32; ++i) tv[i] = W[(size_t)(k0 + 2 * i + (lane >> 5)) * N + n0 + (lane & 31)];
; #pragma unroll
;     for (int i = 0; i < 32; ++i) scr[(2 * i + (lane >> 5)) * 33 + (lane & 31)] = tv[i];
;     asm volatile("s_waitcnt lgkmcnt(0)" ::: "memory");
;     const int c = lane & 7;
; #pragma unroll
;     for (int j = 0; j < 4; ++j) { const int n = (lane >> 3) + 8 * j; const LAS float* s = scr + (8 * c) * 33 + n;
;         u32x4 o; o.x = pk2(s[0 * 33], s[1 * 33]); o.y = pk2(s[2 * 33], s[3 * 33]); o.z = pk2(s[4 * 33], s[5 * 33]); o.w = pk2(s[6 * 33], s[7 * 33]);
;         *(u32x4*)(WT + (size_t)(n0 + n) * K + k0 + 8 * c) = o; }
;     asm volatile("s_waitcnt lgkmcnt(0)" ::: "memory");
; }
; __device__ __forceinline__ void phase0(const Params& p, LAS unsigned char* lds, int gw, int NGW, int wave, int lane) {
;     ...
;     for (int it = gw; it < NIT; it += NGW) {
;         int r = it;
;         if (r < 2 * I_EI) { const int j = r / I_EI; p0_transpose_item(p.in[8] + (size_t)j * 1024 * EIN, 1024, EIN, (bf16_t*)(ws + WS_WEI) + (size_t)j * EINP * 1024, scr, r % I_EI, lane); continue; } r -= 2 * I_EI;
;         if (r < 2 * I_EO) { const int j = r / I_EO; p0_transpose_item(p.in[9] + (size_t)j * 1024 * 1024, 1024, 1024, (bf16_t*)(ws + WS_WEO) + (size_t)j * 1024 * 1024, scr, r % I_EO, lane); continue; } r -= 2 * I_EO;
;         if (r < 2 * I_OI) { const int j = r / I_OI; p0_transpose_item(p.in[21] + (size_t)j * 1024 * OIN, 1024, OIN, (bf16_t*)(ws + WS_WOI) + (size_t)j * OIN * 1024, scr, r % I_OI, lane); continue; } r -= 2 * I_OI;
;         { const int j = r / I_OO; p0_transpose_item(p.in[22] + (size_t)j * 512 * 1024, 512, 1024, (bf16_t*)(ws + WS_WOO) + (size_t)j * 1024 * 512, scr, r % I_OO, lane); }
;     }
.Lwt_o_c1:
	v_subrev_u32_e32 v20, 2112, v0
	v_mov_b32_e32 v4, 0x8000000
	v_mul_hi_u32 v6, v20, v4
	v_mul_u32_u24_e32 v7, 32, v6
	v_sub_u32_e32 v7, v20, v7
	v_lshlrev_b32_e32 v6, 6, v6
	v_lshlrev_b32_e32 v7, 5, v7
	v_mov_b32_e32 v8, 0x1000
	v_mov_b32_e32 v9, 0x800
	v_readlane_b32 s100, v251, 27
	v_readlane_b32 s101, v251, 28
	s_nop 1
	s_add_u32 s100, s100, 0x400000
	s_addc_u32 s101, s101, 0
	v_mov_b32_e32 v10, s100
	v_mov_b32_e32 v11, s101
	s_add_u32 s100, s88, 0x1300000
	s_addc_u32 s101, s89, 0
	v_mov_b32_e32 v12, s100
	v_mov_b32_e32 v13, s101
	s_branch .Lwt_o_body
.Lwt_o_c2:
	v_subrev_u32_e32 v20, 2624, v0
	v_mov_b32_e32 v4, 0x199999a
	v_mul_hi_u32 v6, v20, v4
	v_mul_u32_u24_e32 v7, 160, v6
	v_sub_u32_e32 v7, v20, v7
	v_lshlrev_b32_e32 v6, 6, v6
	v_lshlrev_b32_e32 v7, 5, v7
	v_mov_b32_e32 v8, 0x5000
	v_mov_b32_e32 v9, 0x800
	v_readlane_b32 s100, v251, 51
	v_readlane_b32 s101, v251, 52
	s_nop 1
	s_add_u32 s100, s100, 0x1400000
	s_addc_u32 s101, s101, 0
	v_mov_b32_e32 v10, s100
	v_mov_b32_e32 v11, s101
	s_add_u32 s100, s88, 0x1f00000
	s_addc_u32 s101, s89, 0
	v_mov_b32_e32 v12, s100
	v_mov_b32_e32 v13, s101
	s_branch .Lwt_o_body
.Lwt_o_c3:
	v_subrev_u32_e32 v20, 5184, v0
	v_mov_b32_e32 v4, 0x8000000
	v_mul_hi_u32 v6, v20, v4
	v_mul_u32_u24_e32 v7, 32, v6
	v_sub_u32_e32 v7, v20, v7
	v_lshlrev_b32_e32 v6, 6, v6
	v_lshlrev_b32_e32 v7, 5, v7
	v_mov_b32_e32 v8, 0x1000
	v_mov_b32_e32 v9, 0x400
	v_readlane_b32 s100, v251, 53
	v_readlane_b32 s101, v251, 54
	s_nop 1
	s_add_u32 s100, s100, 0x200000
	s_addc_u32 s101, s101, 0
	v_mov_b32_e32 v10, s100
	v_mov_b32_e32 v11, s101
	s_add_u32 s100, s88, 0x2a00000
	s_addc_u32 s101, s89, 0
	v_mov_b32_e32 v12, s100
	v_mov_b32_e32 v13, s101

; #define LAS __attribute__((address_space(3)))
; __device__ __forceinline__ unsigned pk2(float lo, float hi) { return f2bf(lo) | (f2bf(hi) << 16); }
; __device__ __forceinline__ void p0_transpose_item(const float* W, int K, int N, bf16_t* WT, LAS float* scr, int item, int lane) {
;     const int nblk = N / 32, kb = item / nblk, nb = item % nblk, k0 = 64 * kb, n0 = 32 * nb;
;     float tv[32];
; #pragma unroll
;     for (int i = 0; i < 32; ++i) tv[i] = W[(size_t)(k0 + 2 * i + (lane >> 5)) * N + n0 + (lane & 31)];
; #pragma unroll
;     for (int i = 0; i < 32; ++i) scr[(2 * i + (lane >> 5)) * 33 + (lane & 31)] = tv[i];
;     asm volatile("s_waitcnt lgkmcnt(0)" ::: "memory");
;     const int c = lane & 7;
; #pragma unroll
;     for (int j = 0; j < 4; ++j) { const int n = (lane >> 3) + 8 * j; const LAS float* s = scr + (8 * c) * 33 + n;
;         u32x4 o; o.x = pk2(s[0 * 33], s[1 * 33]); o.y = pk2(s[2 * 33], s[3 * 33]); o.z = pk2(s[4 * 33], s[5 * 33]); o.w = pk2(s[6 * 33], s[7 * 33]);
;         *(u32x4*)(WT + (size_t)(n0 + n) * K + k0 + 8 * c) = o; }
;     asm volatile("s_waitcnt lgkmcnt(0)" ::: "memory");
; }
; __device__ __forceinline__ void phase0(const Params& p, LAS unsigned char* lds, int gw, int NGW, int wave, int lane) {
;     ...
;     for (int it = gw; it < NIT; it += NGW) {
;         int r = it;
;         if (r < 2 * I_EI) { const int j = r / I_EI; p0_transpose_item(p.in[8] + (size_t)j * 1024 * EIN, 1024, EIN, (bf16_t*)(ws + WS_WEI) + (size_t)j * EINP * 1024, scr, r % I_EI, lane); continue; } r -= 2 * I_EI;
;         if (r < 2 * I_EO) { const int j = r / I_EO; p0_transpose_item(p.in[9] + (size_t)j * 1024 * 1024, 1024, 1024, (bf16_t*)(ws + WS_WEO) + (size_t)j * 1024 * 1024, scr, r % I_EO, lane); continue; } r -= 2 * I_EO;
;         if (r < 2 * I_OI) { const int j = r / I_OI; p0_transpose_item(p.in[21] + (size_t)j * 1024 * OIN, 1024, OIN, (bf16_t*)(ws + WS_WOI) + (size_t)j * OIN * 1024, scr, r % I_OI, lane); continue; } r -= 2 * I_OI;
;         { const int j = r / I_OO; p0_transpose_item(p.in[22] + (size_t)j * 512 * 1024, 512, 1024, (bf16_t*)(ws + WS_WOO) + (size_t)j * 1024 * 512, scr, r % I_OO, lane); }
;     }
.Lwt_e_loop:
	v_readfirstlane_b32 s100, v0
	s_nop 1
	s_cmp_ge_u32 s100, 3328
	s_cbranch_scc1 .Lkvc_e_done
	s_cmp_lt_u32 s100, 512
	s_cbranch_scc1 .Lwt_e_c0
	s_cmp_lt_u32 s100, 3072
	s_cbranch_scc1 .Lwt_e_c1
	s_branch .Lwt_e_c2
.Lwt_e_c0:
	v_mov_b32_e32 v20, v0
	v_mov_b32_e32 v4, 0x8000000
	v_mul_hi_u32 v6, v20, v4
	v_mul_u32_u24_e32 v7, 32, v6
	v_sub_u32_e32 v7, v20, v7
	v_lshlrev_b32_e32 v6, 6, v6
	v_lshlrev_b32_e32 v7, 5, v7
	v_mov_b32_e32 v8, 0x1000
	v_mov_b32_e32 v9, 0x800
	v_readlane_b32 s100, v251, 27
	v_readlane_b32 s101, v251, 28
	s_nop 1
	v_mov_b32_e32 v10, s100
	v_mov_b32_e32 v11, s101
	s_add_u32 s100, s88, 0x1100000
	s_addc_u32 s101, s89, 0
	v_mov_b32_e32 v12, s100
	v_mov_b32_e32 v13, s101
	s_branch .Lwt_e_body
.Lwt_e_c1:
	v_subrev_u32_e32 v20, 512, v0
	v_mov_b32_e32 v4, 0x199999a
	v_mul_hi_u32 v6, v20, v4
	v_mul_u32_u24_e32 v7, 160, v6
	v_sub_u32_e32 v7, v20, v7
	v_lshlrev_b32_e32 v6, 6, v6
	v_lshlrev_b32_e32 v7, 5, v7
	v_mov_b32_e32 v8, 0x5000
	v_mov_b32_e32 v9, 0x800
	v_readlane_b32 s100, v251, 51
	v_readlane_b32 s101, v251, 52
	s_nop 1
	v_mov_b32_e32 v10, s100
	v_mov_b32_e32 v11, s101
	s_add_u32 s100, s88, 0x1500000
	s_addc_u32 s101, s89, 0
	v_mov_b32_e32 v12, s100
	v_mov_b32_e32 v13, s101
	s_branch .Lwt_e_body
.Lwt_e_c2:
	v_subrev_u32_e32 v20, 3072, v0
	v_mov_b32_e32 v4, 0x8000000
	v_mul_hi_u32 v6, v20, v4
	v_mul_u32_u24_e32 v7, 32, v6
	v_sub_u32_e32 v7, v20, v7
	v_lshlrev_b32_e32 v6, 6, v6
	v_lshlrev_b32_e32 v7, 5, v7
	v_mov_b32_e32 v8, 0x1000
	v_mov_b32_e32 v9, 0x400
	v_readlane_b32 s100, v251, 53
	v_readlane_b32 s101, v251, 54
	s_nop 1
	v_mov_b32_e32 v10, s100
	v_mov_b32_e32 v11, s101
	s_add_u32 s100, s88, 0x2900000
	s_addc_u32 s101, s89, 0
	v_mov_b32_e32 v12, s100
	v_mov_b32_e32 v13, s101
